# rwkv2 role-2 gamma segment rewritten: batched LDS reads, back-to-back MFMAs, then writes
# speedup vs baseline: 1.0764x; 1.0128x over previous
; #define LBARW() do { if (PROBE_ROLE >= 0 && wave == PROBE_ROLE) { const unsigned long long tb_ = __builtin_amdgcn_s_memrealtime(); LBAR(); twait += __builtin_amdgcn_s_memrealtime() - tb_; } else { LBAR(); } } while (0)
; __device__ unsigned long long rwkv2_phase(const Params& p, unsigned char* smem) {
;     ...
;             for (int pc = 0; pc <= NCH + 1; ++pc) {
;                 const int cm = pc - 1; const bool act = (cm >= 0 && cm < NCH);
;                 int ln_ = lane; asm volatile("" : "+v"(ln_)); const int lane = ln_, l15 = ln_ & 15, lq = ln_ >> 4; (void)lane;
;     ...
;                     }
;                 }
;                 LBARW();
;             }
.LBB0_878:
	s_and_b64 vcc, exec, s[26:27]
	s_cbranch_vccz .LBB0_946
	s_mov_b32 s30, 0
	s_branch .LBB0_882
.LBB0_881:
	s_waitcnt lgkmcnt(0)
	s_barrier
	s_add_i32 s30, s30, 1
	s_waitcnt lgkmcnt(0)
	v_mov_b64_e32 v[44:45], v[32:33]
	v_mov_b64_e32 v[48:49], v[28:29]
	v_mov_b64_e32 v[52:53], v[24:25]
	v_mov_b64_e32 v[68:69], v[20:21]
	v_mov_b64_e32 v[92:93], v[16:17]
	v_mov_b64_e32 v[96:97], v[12:13]
	s_cmpk_eq_i32 s30, 0x102
	v_mov_b64_e32 v[42:43], v[30:31]
	v_mov_b64_e32 v[46:47], v[26:27]
	v_mov_b64_e32 v[50:51], v[22:23]
	v_mov_b64_e32 v[66:67], v[18:19]
	v_mov_b64_e32 v[90:91], v[14:15]
	v_mov_b64_e32 v[94:95], v[10:11]
	s_cbranch_scc1 .LBB0_946

; __device__ __forceinline__ u16 f2bf(float f) { return (u16)(pk2(f, 0.f) & 0xffffu); }
; __device__ __forceinline__ float bf2f(u16 v) { return __uint_as_float(((unsigned)v) << 16); }
; #define MFMA16(a, b, c) __builtin_amdgcn_mfma_f32_16x16x32_bf16((a), (b), (c), 0, 0, 0)
; __device__ unsigned long long rwkv2_phase(const Params& p, unsigned char* smem) {
;     ...
;                 if (act) {
;                     unsigned char* set2 = S2 + (cm & 1) * 16896;
;                     const bf16x8 mrbf = *(const bf16x8*)(Mxb + l15 * 32 + 8 * lq);
;                     if (wave == 4) {
;                         u16* Rh = (u16*)(set2 + 2304); float* Yk = (float*)(set2 + 12800);
;                         const u16* VT = (const u16*)(S1b + (cm % 3) * 10560 + 8192);
;                         const bf16x8 mrkf = *(const bf16x8*)(Mxb + 512 + l15 * 32 + 8 * lq);
; #pragma unroll
;                         for (int nt = 0; nt < 4; ++nt) { u32x4 az = {0u, 0u, 0u, 0u}, vz = {0u, 0u, 0u, 0u};
;                             if (lq < 2) { az = *(const u32x4*)(AhT + (16 * nt + l15) * 16 + 8 * lq); vz = *(const u32x4*)(VT + (16 * nt + l15) * 16 + 8 * lq); }
;                             const f32x4 d = MFMA16(mrbf, as_frag(az), ((f32x4){0.f, 0.f, 0.f, 0.f})), e = MFMA16(mrkf, as_frag(vz), ((f32x4){0.f, 0.f, 0.f, 0.f}));
; #pragma unroll
;                             for (int r = 0; r < 4; ++r) { const int o = (4 * lq + r) * 72 + 16 * nt + l15; Rh[o] = f2bf(d[r] + bf2f(Rt[o])); Yk[(4 * lq + r) * 64 + 16 * nt + l15] = e[r]; } }
;                     } else {
;                         float* Yh = (float*)(set2 + 8704);
; #pragma unroll
;                         for (int nt = 0; nt < 4; ++nt) { u32x4 vz = {0u, 0u, 0u, 0u}; if (lq < 2) vz = *(const u32x4*)(VhT + (16 * nt + l15) * 16 + 8 * lq);
;                             const f32x4 d = MFMA16(mrbf, as_frag(vz), ((f32x4){0.f, 0.f, 0.f, 0.f}));
; #pragma unroll
;                             for (int r = 0; r < 4; ++r) Yh[(4 * lq + r) * 64 + 16 * nt + l15] = d[r]; }
.LBB0_926:
	s_andn2_b64 vcc, exec, s[26:27]
	s_cbranch_vccnz .LBB0_881
	v_lshlrev_b32_e32 v4, 6, v72
	v_lshlrev_b32_e32 v42, 4, v73
	v_add3_u32 v4, s96, v4, v42
	ds_read_b128 v[42:45], v4
	s_mulk_i32 s69, 0x4200
	s_add_i32 s69, s69, 0
	v_lshlrev_b32_e32 v5, 3, v73
	s_add_i32 s69, s69, 0x19d40
	v_lshlrev_b32_e32 v3, 5, v72
	s_mov_b64 s[28:29], -1
	s_and_b64 vcc, exec, s[60:61]
	v_cmp_gt_i32_e64 s[26:27], 2, v73
	v_lshlrev_b32_e32 v4, 1, v5
	s_cbranch_vccz .LBB0_937
	s_add_i32 s28, 0, 0x18340
	v_add3_u32 v5, s28, v3, v4
	v_mov_b32_e32 v186, 0
	v_mov_b32_e32 v187, 0
	v_mov_b32_e32 v188, 0
	v_mov_b32_e32 v189, 0
	v_mov_b32_e32 v190, 0
	v_mov_b32_e32 v191, 0
	v_mov_b32_e32 v192, 0
	v_mov_b32_e32 v193, 0
	v_mov_b32_e32 v194, 0
	v_mov_b32_e32 v195, 0
	v_mov_b32_e32 v196, 0
	v_mov_b32_e32 v197, 0
	v_mov_b32_e32 v198, 0
	v_mov_b32_e32 v199, 0
	v_mov_b32_e32 v200, 0
	v_mov_b32_e32 v201, 0
	s_and_saveexec_b64 s[28:29], s[26:27]
	ds_read_b128 v[186:189], v5
	ds_read_b128 v[190:193], v5 offset:512
	ds_read_b128 v[194:197], v5 offset:1024
	ds_read_b128 v[198:201], v5 offset:1536
	s_or_b64 exec, exec, s[28:29]
	v_lshlrev_b32_e32 v47, 10, v73
	v_lshlrev_b32_e32 v52, 2, v72
	v_add3_u32 v52, s69, v47, v52
	s_waitcnt lgkmcnt(0)
	v_mfma_f32_16x16x32_bf16 v[186:189], v[42:45], v[186:189], 0
	v_mfma_f32_16x16x32_bf16 v[190:193], v[42:45], v[190:193], 0
	v_mfma_f32_16x16x32_bf16 v[194:197], v[42:45], v[194:197], 0
	v_mfma_f32_16x16x32_bf16 v[198:201], v[42:45], v[198:201], 0
	v_add_u32_e32 v50, 64, v52
	v_add_u32_e32 v47, 0x80, v52
	v_add_u32_e32 v5, 0xc0, v52
	s_nop 3
	ds_write2st64_b32 v52, v186, v187 offset0:34 offset1:35
	ds_write2st64_b32 v52, v188, v189 offset0:36 offset1:37
	ds_write2st64_b32 v50, v190, v191 offset0:34 offset1:35
	ds_write2st64_b32 v50, v192, v193 offset0:36 offset1:37
	ds_write2st64_b32 v47, v194, v195 offset0:34 offset1:35
	ds_write2st64_b32 v47, v196, v197 offset0:36 offset1:37
	ds_write2st64_b32 v5, v198, v199 offset0:34 offset1:35
	ds_write2st64_b32 v5, v200, v201 offset0:36 offset1:37
	s_branch .LBB0_881
; __device__ __forceinline__ u16 f2bf(float f) { return (u16)(pk2(f, 0.f) & 0xffffu); }
; __device__ __forceinline__ float bf2f(u16 v) { return __uint_as_float(((unsigned)v) << 16); }
; #define MFMA16(a, b, c) __builtin_amdgcn_mfma_f32_16x16x32_bf16((a), (b), (c), 0, 0, 0)
; __device__ unsigned long long rwkv2_phase(const Params& p, unsigned char* smem) {
;     ...
;                 if (act) {
;                     unsigned char* set2 = S2 + (cm & 1) * 16896;
;                     const bf16x8 mrbf = *(const bf16x8*)(Mxb + l15 * 32 + 8 * lq);
;                     if (wave == 4) {
;                         u16* Rh = (u16*)(set2 + 2304); float* Yk = (float*)(set2 + 12800);
;                         const u16* VT = (const u16*)(S1b + (cm % 3) * 10560 + 8192);
;                         const bf16x8 mrkf = *(const bf16x8*)(Mxb + 512 + l15 * 32 + 8 * lq);
; #pragma unroll
;                         for (int nt = 0; nt < 4; ++nt) { u32x4 az = {0u, 0u, 0u, 0u}, vz = {0u, 0u, 0u, 0u};
;                             if (lq < 2) { az = *(const u32x4*)(AhT + (16 * nt + l15) * 16 + 8 * lq); vz = *(const u32x4*)(VT + (16 * nt + l15) * 16 + 8 * lq); }
;                             const f32x4 d = MFMA16(mrbf, as_frag(az), ((f32x4){0.f, 0.f, 0.f, 0.f})), e = MFMA16(mrkf, as_frag(vz), ((f32x4){0.f, 0.f, 0.f, 0.f}));
; #pragma unroll
;                             for (int r = 0; r < 4; ++r) { const int o = (4 * lq + r) * 72 + 16 * nt + l15; Rh[o] = f2bf(d[r] + bf2f(Rt[o])); Yk[(4 * lq + r) * 64 + 16 * nt + l15] = e[r]; } }
.LBB0_937:
	s_and_b64 vcc, exec, s[28:29]
	s_cbranch_vccz .LBB0_881
	s_mul_hi_i32 s26, s68, 0x55555556
	s_lshr_b32 s27, s26, 31
	s_add_i32 s26, s26, s27
	s_mul_i32 s26, s26, 3
	s_sub_i32 s26, s68, s26
	s_mulk_i32 s26, 0x2940
	v_lshlrev_b32_e32 v3, 1, v3
	v_readlane_b32 s16, v250, 3
	s_add_i32 s26, s26, 0
	s_add_i32 s26, s26, 0xe380
	v_add3_u32 v3, s16, v3, v4
	ds_read_b128 v[46:49], v3
	v_add_u32_e32 v5, s26, v4
	s_add_i32 s26, 0, 0x17b40
	v_add_u32_e32 v3, s26, v4
	v_lshlrev_b32_e32 v4, 4, v72
	v_lshlrev_b32_e32 v4, 1, v4
	v_cmp_gt_i32_e32 vcc, 2, v73
	v_add_u32_e32 v3, v3, v4
	v_add_u32_e32 v4, v5, v4
	v_mov_b32_e32 v186, 0
	v_mov_b32_e32 v187, 0
	v_mov_b32_e32 v188, 0
	v_mov_b32_e32 v189, 0
	v_mov_b32_e32 v190, 0
	v_mov_b32_e32 v191, 0
	v_mov_b32_e32 v192, 0
	v_mov_b32_e32 v193, 0
	v_mov_b32_e32 v194, 0
	v_mov_b32_e32 v195, 0
	v_mov_b32_e32 v196, 0
	v_mov_b32_e32 v197, 0
	v_mov_b32_e32 v198, 0
	v_mov_b32_e32 v199, 0
	v_mov_b32_e32 v200, 0
	v_mov_b32_e32 v201, 0
	v_mov_b32_e32 v202, 0
	v_mov_b32_e32 v203, 0
	v_mov_b32_e32 v204, 0
	v_mov_b32_e32 v205, 0
	v_mov_b32_e32 v206, 0
	v_mov_b32_e32 v207, 0
	v_mov_b32_e32 v208, 0
	v_mov_b32_e32 v209, 0
	v_mov_b32_e32 v210, 0
	v_mov_b32_e32 v211, 0
	v_mov_b32_e32 v212, 0
	v_mov_b32_e32 v213, 0
	v_mov_b32_e32 v214, 0
	v_mov_b32_e32 v215, 0
	v_mov_b32_e32 v216, 0
	v_mov_b32_e32 v217, 0
	s_and_saveexec_b64 s[26:27], vcc
	ds_read_b128 v[186:189], v3
	ds_read_b128 v[190:193], v4 offset:8192
	ds_read_b128 v[194:197], v3 offset:512
	ds_read_b128 v[198:201], v4 offset:8704
	ds_read_b128 v[202:205], v3 offset:1024
	ds_read_b128 v[206:209], v4 offset:9216
	ds_read_b128 v[210:213], v3 offset:1536
	ds_read_b128 v[214:217], v4 offset:9728
	s_or_b64 exec, exec, s[26:27]
	v_mul_lo_u32 v67, v73, s50
	v_add_lshl_u32 v60, v67, v72, 1
	v_lshl_or_b32 v56, v73, 2, 1
	v_mul_lo_u32 v57, v56, s52
	v_add_lshl_u32 v61, v57, v72, 1
	v_add_u32_e32 v62, 0x90, v61
	v_add_u32_e32 v63, 0x90, v62
	v_add_u32_e32 v64, s31, v60
	v_add_u32_e32 v65, s31, v61
	v_add_u32_e32 v66, s31, v62
	v_add_u32_e32 v67, s31, v63
	ds_read_u16 v218, v64 offset:42112
	ds_read_u16 v219, v65 offset:42112
	ds_read_u16 v220, v66 offset:42112
	ds_read_u16 v221, v67 offset:42112
	ds_read_u16 v222, v64 offset:42144
	ds_read_u16 v223, v65 offset:42144
	ds_read_u16 v224, v66 offset:42144
	ds_read_u16 v225, v67 offset:42144
	ds_read_u16 v226, v64 offset:42176
	ds_read_u16 v227, v65 offset:42176
	ds_read_u16 v228, v66 offset:42176
	ds_read_u16 v229, v67 offset:42176
	ds_read_u16 v230, v64 offset:42208
	ds_read_u16 v231, v65 offset:42208
	ds_read_u16 v232, v66 offset:42208
	ds_read_u16 v233, v67 offset:42208
	v_add_u32_e32 v68, s69, v60
	v_add_u32_e32 v69, s69, v61
	v_add_u32_e32 v70, s69, v62
	v_add_u32_e32 v71, s69, v63
	v_lshl_add_u32 v51, v72, 2, s69
	v_lshlrev_b32_e32 v52, 10, v73
	v_add_u32_e32 v5, v51, v52
	s_waitcnt lgkmcnt(0)
	v_mfma_f32_16x16x32_bf16 v[186:189], v[42:45], v[186:189], 0
	v_mfma_f32_16x16x32_bf16 v[190:193], v[46:49], v[190:193], 0
	v_mfma_f32_16x16x32_bf16 v[194:197], v[42:45], v[194:197], 0
	v_mfma_f32_16x16x32_bf16 v[198:201], v[46:49], v[198:201], 0
	v_mfma_f32_16x16x32_bf16 v[202:205], v[42:45], v[202:205], 0
	v_mfma_f32_16x16x32_bf16 v[206:209], v[46:49], v[206:209], 0
	v_mfma_f32_16x16x32_bf16 v[210:213], v[42:45], v[210:213], 0
	v_mfma_f32_16x16x32_bf16 v[214:217], v[46:49], v[214:217], 0
	v_lshlrev_b32_e32 v218, 16, v218
	v_lshlrev_b32_e32 v219, 16, v219
	v_lshlrev_b32_e32 v220, 16, v220
	v_lshlrev_b32_e32 v221, 16, v221
	v_lshlrev_b32_e32 v222, 16, v222
	v_lshlrev_b32_e32 v223, 16, v223
	v_lshlrev_b32_e32 v224, 16, v224
	v_lshlrev_b32_e32 v225, 16, v225
	v_lshlrev_b32_e32 v226, 16, v226
	v_lshlrev_b32_e32 v227, 16, v227
	v_lshlrev_b32_e32 v228, 16, v228
	v_lshlrev_b32_e32 v229, 16, v229
	v_lshlrev_b32_e32 v230, 16, v230
	v_lshlrev_b32_e32 v231, 16, v231
	v_lshlrev_b32_e32 v232, 16, v232
	v_lshlrev_b32_e32 v233, 16, v233
	v_add_f32_e32 v218, v186, v218
	v_cvt_pk_bf16_f32 v218, v218, v2
	ds_write_b16 v68, v218 offset:2304
	ds_write_b32 v5, v190 offset:12800
	v_add_f32_e32 v219, v187, v219
	v_cvt_pk_bf16_f32 v219, v219, v2
	ds_write_b16 v69, v219 offset:2304
	ds_write_b32 v5, v191 offset:13056
	v_add_f32_e32 v220, v188, v220
	v_cvt_pk_bf16_f32 v220, v220, v2
	ds_write_b16 v70, v220 offset:2304
	ds_write_b32 v5, v192 offset:13312
	v_add_f32_e32 v221, v189, v221
	v_cvt_pk_bf16_f32 v221, v221, v2
	ds_write_b16 v71, v221 offset:2304
	ds_write_b32 v5, v193 offset:13568
	v_add_f32_e32 v222, v194, v222
	v_cvt_pk_bf16_f32 v222, v222, v2
	ds_write_b16 v68, v222 offset:2336
	ds_write_b32 v5, v198 offset:12864
	v_add_f32_e32 v223, v195, v223
	v_cvt_pk_bf16_f32 v223, v223, v2
	ds_write_b16 v69, v223 offset:2336
	ds_write_b32 v5, v199 offset:13120
	v_add_f32_e32 v224, v196, v224
	v_cvt_pk_bf16_f32 v224, v224, v2
	ds_write_b16 v70, v224 offset:2336
	ds_write_b32 v5, v200 offset:13376
	v_add_f32_e32 v225, v197, v225
	v_cvt_pk_bf16_f32 v225, v225, v2
	ds_write_b16 v71, v225 offset:2336
	ds_write_b32 v5, v201 offset:13632
	v_add_f32_e32 v226, v202, v226
	v_cvt_pk_bf16_f32 v226, v226, v2
	ds_write_b16 v68, v226 offset:2368
	ds_write_b32 v5, v206 offset:12928
	v_add_f32_e32 v227, v203, v227
	v_cvt_pk_bf16_f32 v227, v227, v2
	ds_write_b16 v69, v227 offset:2368
	ds_write_b32 v5, v207 offset:13184
	v_add_f32_e32 v228, v204, v228
	v_cvt_pk_bf16_f32 v228, v228, v2
	ds_write_b16 v70, v228 offset:2368
	ds_write_b32 v5, v208 offset:13440
	v_add_f32_e32 v229, v205, v229
	v_cvt_pk_bf16_f32 v229, v229, v2
	ds_write_b16 v71, v229 offset:2368
	ds_write_b32 v5, v209 offset:13696
	v_add_f32_e32 v230, v210, v230
	v_cvt_pk_bf16_f32 v230, v230, v2
	ds_write_b16 v68, v230 offset:2400
	ds_write_b32 v5, v214 offset:12992
	v_add_f32_e32 v231, v211, v231
	v_cvt_pk_bf16_f32 v231, v231, v2
	ds_write_b16 v69, v231 offset:2400
	ds_write_b32 v5, v215 offset:13248
	v_add_f32_e32 v232, v212, v232
	v_cvt_pk_bf16_f32 v232, v232, v2
	ds_write_b16 v70, v232 offset:2400
	ds_write_b32 v5, v216 offset:13504
	v_add_f32_e32 v233, v213, v233
	v_cvt_pk_bf16_f32 v233, v233, v2
	ds_write_b16 v71, v233 offset:2400
	ds_write_b32 v5, v217 offset:13760
	s_branch .LBB0_881
